# GEMM unit start: skip the full vmcnt(0) drain and the redundant first zeroing of the 128 accumulators when the K-loop runs (on top of the chain-order MFMAs, hand-off trim, ph0 changes)
# baseline (speedup 1.0000x reference)
; template <class Epi, class Sched, bool ALIGN_EPI = false, bool SP2 = false>
; __device__ __forceinline__ void gemm_phase(PG8_LAS unsigned char* lds, const Gemm g, const Sched& S, const Epi& E) {
;     ...
;     f32x4 acc[2][2][4][2];
; #pragma unroll
;     for (int a = 0; a < 2; ++a)
; #pragma unroll
;         for (int b = 0; b < 2; ++b)
; #pragma unroll
;             for (int m = 0; m < 4; ++m)
; #pragma unroll
;                 for (int n = 0; n < 2; ++n) acc[a][b][m][n] = (f32x4){0.f, 0.f, 0.f, 0.f};
;     ...
;     for (;;) {
;         const bool has_next = S.next(ui + 1, nxt);
;         const char* nA = has_next ? (const char*)g.A + (size_t)nxt.pm * tstep : cA; const char* nB = has_next ? (const char*)g.Bt + (size_t)nxt.pn * tstep : cB;
;         for (int t = 0; t < nt; t += 2) {
;             if constexpr (Epi::KHOOK) { if (E.khook_at(t)) E.khook(acc, cur, t, wr, wc, fr, fq); }
;             const bool last = (t == nt - 2);
;             const char* a1 = cA + (size_t)(t + 1) * kstep;
;             const char* a2 = last ? nA : cA + (size_t)(t + 2) * kstep; const char* b2 = last ? nB : cB + (size_t)(t + 2) * kstep;
;             const char* a3 = a2 + kstep; const char* b3 = b2 + kstep;
.LBB0_52:
	s_andn2_b64 vcc, exec, s[14:15]
	s_cbranch_vccz .Lunit_kloop
	s_waitcnt vmcnt(0)
	v_mov_b32_e32 v119, 0
	v_mov_b32_e32 v118, 0
	v_mov_b32_e32 v117, 0
	v_mov_b32_e32 v116, v119
	v_mov_b32_e32 v123, 0
	v_mov_b32_e32 v122, 0
	v_mov_b32_e32 v121, 0
	v_mov_b32_e32 v120, v119
	v_mov_b32_e32 v103, 0
	v_mov_b32_e32 v102, 0
	v_mov_b32_e32 v101, 0
	v_mov_b32_e32 v100, v119
	v_mov_b32_e32 v107, 0
	v_mov_b32_e32 v106, 0
	v_mov_b32_e32 v105, 0
	v_mov_b32_e32 v104, v119
	v_mov_b32_e32 v79, 0
	v_mov_b32_e32 v78, 0
	v_mov_b32_e32 v77, 0
	v_mov_b32_e32 v76, v119
	v_mov_b32_e32 v83, 0
	v_mov_b32_e32 v82, 0
	v_mov_b32_e32 v81, 0
	v_mov_b32_e32 v80, v119
	v_mov_b32_e32 v47, 0
	v_mov_b32_e32 v46, 0
	v_mov_b32_e32 v45, 0
	v_mov_b32_e32 v44, v119
	v_mov_b32_e32 v51, 0
	v_mov_b32_e32 v50, 0
	v_mov_b32_e32 v49, 0
	v_mov_b32_e32 v48, v119
	v_mov_b32_e32 v127, 0
	v_mov_b32_e32 v126, 0
	v_mov_b32_e32 v125, 0
	v_mov_b32_e32 v124, v119
	v_mov_b32_e32 v131, 0
	v_mov_b32_e32 v130, 0
	v_mov_b32_e32 v129, 0
	v_mov_b32_e32 v128, v119
	v_mov_b32_e32 v111, 0
	v_mov_b32_e32 v110, 0
	v_mov_b32_e32 v109, 0
	v_mov_b32_e32 v108, v119
	v_mov_b32_e32 v115, 0
	v_mov_b32_e32 v114, 0
	v_mov_b32_e32 v113, 0
	v_mov_b32_e32 v112, v119
	v_mov_b32_e32 v95, 0
	v_mov_b32_e32 v94, 0
	v_mov_b32_e32 v93, 0
	v_mov_b32_e32 v92, v119
	v_mov_b32_e32 v99, 0
	v_mov_b32_e32 v98, 0
	v_mov_b32_e32 v97, 0
	v_mov_b32_e32 v96, v119
	v_mov_b32_e32 v71, 0
	v_mov_b32_e32 v70, 0
	v_mov_b32_e32 v69, 0
	v_mov_b32_e32 v68, v119
	v_mov_b32_e32 v75, 0
	v_mov_b32_e32 v74, 0
	v_mov_b32_e32 v73, 0
	v_mov_b32_e32 v72, v119
	v_mov_b32_e32 v63, 0
	v_mov_b32_e32 v62, 0
	v_mov_b32_e32 v61, 0
	v_mov_b32_e32 v60, v119
	v_mov_b32_e32 v67, 0
	v_mov_b32_e32 v66, 0
	v_mov_b32_e32 v65, 0
	v_mov_b32_e32 v64, v119
	v_mov_b32_e32 v39, 0
	v_mov_b32_e32 v38, 0
	v_mov_b32_e32 v37, 0
	v_mov_b32_e32 v36, v119
	v_mov_b32_e32 v43, 0
	v_mov_b32_e32 v42, 0
	v_mov_b32_e32 v41, 0
	v_mov_b32_e32 v40, v119
	v_mov_b32_e32 v23, 0
	v_mov_b32_e32 v22, 0
	v_mov_b32_e32 v21, 0
	v_mov_b32_e32 v20, v119
	v_mov_b32_e32 v27, 0
	v_mov_b32_e32 v26, 0
	v_mov_b32_e32 v25, 0
	v_mov_b32_e32 v24, v119
	v_mov_b32_e32 v7, 0
	v_mov_b32_e32 v6, 0
	v_mov_b32_e32 v5, 0
	v_mov_b32_e32 v4, v119
	v_mov_b32_e32 v11, 0
	v_mov_b32_e32 v10, 0
	v_mov_b32_e32 v9, 0
	v_mov_b32_e32 v8, v119
	v_mov_b32_e32 v87, 0
	v_mov_b32_e32 v86, 0
	v_mov_b32_e32 v85, 0
	v_mov_b32_e32 v84, v119
	v_mov_b32_e32 v91, 0
	v_mov_b32_e32 v90, 0
	v_mov_b32_e32 v89, 0
	v_mov_b32_e32 v88, v119
	v_mov_b32_e32 v55, 0
	v_mov_b32_e32 v54, 0
	v_mov_b32_e32 v53, 0
	v_mov_b32_e32 v52, v119
	v_mov_b32_e32 v59, 0
	v_mov_b32_e32 v58, 0
	v_mov_b32_e32 v57, 0
	v_mov_b32_e32 v56, v119
	v_mov_b32_e32 v31, 0
	v_mov_b32_e32 v30, 0
	v_mov_b32_e32 v29, 0
	v_mov_b32_e32 v28, v119
	v_mov_b32_e32 v35, 0
	v_mov_b32_e32 v34, 0
	v_mov_b32_e32 v33, 0
	v_mov_b32_e32 v32, v119
	v_mov_b32_e32 v15, 0
	v_mov_b32_e32 v14, 0
	v_mov_b32_e32 v13, 0
	v_mov_b32_e32 v12, v119
	v_mov_b32_e32 v19, 0
	v_mov_b32_e32 v18, 0
	v_mov_b32_e32 v17, 0
	v_mov_b32_e32 v16, v119
	s_branch .LBB0_58
.Lunit_kloop:
	s_lshl_b32 s57, s54, 8
	s_lshl_b32 s2, s53, 8
	s_or_b32 s58, s57, 0x80
	s_or_b32 s59, s2, s50
	s_add_u32 s60, s30, 0x100
	s_addc_u32 s61, s31, 0
	s_add_u32 s30, s28, 0x80
	v_mov_b32_e32 v2, v1
	v_mov_b32_e32 v3, v1
	s_addc_u32 s31, s29, 0
	v_mov_b32_e32 v0, v1
	v_mov_b64_e32 v[18:19], v[2:3]
	v_mov_b64_e32 v[14:15], v[2:3]
	v_mov_b64_e32 v[34:35], v[2:3]
	v_mov_b64_e32 v[30:31], v[2:3]
	v_mov_b64_e32 v[58:59], v[2:3]
	v_mov_b64_e32 v[54:55], v[2:3]
	v_mov_b64_e32 v[90:91], v[2:3]
	v_mov_b64_e32 v[86:87], v[2:3]
	v_mov_b64_e32 v[10:11], v[2:3]
	v_mov_b64_e32 v[6:7], v[2:3]
	v_mov_b64_e32 v[26:27], v[2:3]
	v_mov_b64_e32 v[22:23], v[2:3]
	v_mov_b64_e32 v[42:43], v[2:3]
	v_mov_b64_e32 v[38:39], v[2:3]
	v_mov_b64_e32 v[66:67], v[2:3]
	v_mov_b64_e32 v[62:63], v[2:3]
	v_mov_b64_e32 v[74:75], v[2:3]
	v_mov_b64_e32 v[70:71], v[2:3]
	v_mov_b64_e32 v[98:99], v[2:3]
	v_mov_b64_e32 v[94:95], v[2:3]
	v_mov_b64_e32 v[114:115], v[2:3]
	v_mov_b64_e32 v[110:111], v[2:3]
	v_mov_b64_e32 v[130:131], v[2:3]
	v_mov_b64_e32 v[126:127], v[2:3]
	v_mov_b64_e32 v[50:51], v[2:3]
	v_mov_b64_e32 v[46:47], v[2:3]
	v_mov_b64_e32 v[82:83], v[2:3]
	v_mov_b64_e32 v[78:79], v[2:3]
	v_mov_b64_e32 v[106:107], v[2:3]
	v_mov_b64_e32 v[102:103], v[2:3]
	v_mov_b64_e32 v[122:123], v[2:3]
	v_mov_b64_e32 v[118:119], v[2:3]
	v_lshl_add_u64 v[204:205], s[30:31], 0, v[198:199]
	v_lshl_add_u64 v[206:207], s[30:31], 0, v[200:201]
	s_mov_b32 s34, 0
	s_mov_b64 s[30:31], 0
	v_mov_b64_e32 v[16:17], v[0:1]
	v_mov_b64_e32 v[12:13], v[0:1]
	v_mov_b64_e32 v[32:33], v[0:1]
	v_mov_b64_e32 v[28:29], v[0:1]
	v_mov_b64_e32 v[56:57], v[0:1]
	v_mov_b64_e32 v[52:53], v[0:1]
	v_mov_b64_e32 v[88:89], v[0:1]
	v_mov_b64_e32 v[84:85], v[0:1]
	v_mov_b64_e32 v[8:9], v[0:1]
	v_mov_b64_e32 v[4:5], v[0:1]
	v_mov_b64_e32 v[24:25], v[0:1]
	v_mov_b64_e32 v[20:21], v[0:1]
	v_mov_b64_e32 v[40:41], v[0:1]
	v_mov_b64_e32 v[36:37], v[0:1]
	v_mov_b64_e32 v[64:65], v[0:1]
	v_mov_b64_e32 v[60:61], v[0:1]
	v_mov_b64_e32 v[72:73], v[0:1]
	v_mov_b64_e32 v[68:69], v[0:1]
	v_mov_b64_e32 v[96:97], v[0:1]
	v_mov_b64_e32 v[92:93], v[0:1]
	v_mov_b64_e32 v[112:113], v[0:1]
	v_mov_b64_e32 v[108:109], v[0:1]
	v_mov_b64_e32 v[128:129], v[0:1]
	v_mov_b64_e32 v[124:125], v[0:1]
	v_mov_b64_e32 v[48:49], v[0:1]
	v_mov_b64_e32 v[44:45], v[0:1]
	v_mov_b64_e32 v[80:81], v[0:1]
	v_mov_b64_e32 v[76:77], v[0:1]
	v_mov_b64_e32 v[104:105], v[0:1]
	v_mov_b64_e32 v[100:101], v[0:1]
	v_mov_b64_e32 v[120:121], v[0:1]
	v_mov_b64_e32 v[116:117], v[0:1]
